# norm phases: split-K partial folds issue all piece loads back-to-back with counted vmcnt (was 16/44 serialized vmcnt(0) round trips)
# speedup vs baseline: 1.0028x; 1.0028x over previous
; __device__ __forceinline__ void norm_phase(const float* hl, const float* hc, const float* __restrict__ g, const float* __restrict__ modl, int sh_chunk, bf16_t* XN, int gw, int NGW, int lane, int nrows, const float* part, int npieces) {
;     ...
;         const float* xr = row < MLAT ? hl + (size_t)row * D : hc + (size_t)(row - MLAT) * D;
;         const int mi = row < MLAT ? (row >> 13) : 4;
;         const float* shift = modl + mi * 9216 + sh_chunk * 1024; const float* scale = shift + 1024;
;         f32x4 v[4]; float s = 0.f;
; #pragma unroll
;         for (int j = 0; j < 4; ++j) v[j] = *(const f32x4*)(xr + 4 * lane + 256 * j);
;         if (row >= MLAT && npieces > 0) {
;             for (int p = 0; p < npieces; ++p) { const float* pr = part + ((size_t)p * 1024 + (row - MLAT)) * D + 4 * lane;
; #pragma unroll
;                 for (int j = 0; j < 4; ++j) v[j] = v[j] + *(const f32x4*)(pr + 256 * j); }
; #pragma unroll
;             for (int j = 0; j < 4; ++j) *(f32x4*)(const_cast<float*>(xr) + 4 * lane + 256 * j) = v[j];
;         }
.LBB0_21:
	s_add_i32 s16, s20, 0xffff8000
	s_ashr_i32 s21, s20, 31
	s_cmp_lt_i32 s20, 0x8000
	s_cselect_b64 s[34:35], -1, 0
	s_and_b64 s[38:39], s[34:35], exec
	s_cselect_b32 s39, s21, 0
	s_cselect_b32 s38, s20, s16
	s_cselect_b32 s40, s9, s37
	s_cselect_b32 s41, s8, s36
	s_lshl_b64 s[38:39], s[38:39], 12
	s_add_u32 s38, s41, s38
	s_addc_u32 s39, s40, s39
	v_lshl_add_u64 v[40:41], v[34:35], 2, s[38:39]
	global_load_dwordx4 v[26:29], v[40:41], off
	global_load_dwordx4 v[22:25], v[40:41], off offset:1024
	global_load_dwordx4 v[18:21], v[40:41], off offset:2048
	global_load_dwordx4 v[30:33], v[40:41], off offset:3072
	s_or_b64 s[34:35], s[14:15], s[34:35]
	s_and_b64 vcc, exec, s[34:35]
	s_cbranch_vccnz .LBB0_20
	s_lshl_b64 s[34:35], s[16:17], 12
	v_lshl_add_u64 v[42:43], v[36:37], 0, s[34:35]
	s_mov_b32 s35, 0
	global_load_dwordx4 v[48:51], v[42:43], off
	global_load_dwordx4 v[52:55], v[42:43], off offset:1024
	global_load_dwordx4 v[56:59], v[42:43], off offset:2048
	global_load_dwordx4 v[60:63], v[42:43], off offset:3072
	s_mov_b32 s34, 0x400000
	v_lshl_add_u64 v[44:45], v[42:43], 0, s[34:35]
	global_load_dwordx4 v[64:67], v[44:45], off
	global_load_dwordx4 v[68:71], v[44:45], off offset:1024
	global_load_dwordx4 v[72:75], v[44:45], off offset:2048
	global_load_dwordx4 v[76:79], v[44:45], off offset:3072
	s_mov_b32 s34, 0x800000
	v_lshl_add_u64 v[46:47], v[42:43], 0, s[34:35]
	global_load_dwordx4 v[80:83], v[46:47], off
	global_load_dwordx4 v[84:87], v[46:47], off offset:1024
	global_load_dwordx4 v[88:91], v[46:47], off offset:2048
	global_load_dwordx4 v[92:95], v[46:47], off offset:3072
	s_mov_b32 s34, 0xc00000
	v_lshl_add_u64 v[44:45], v[42:43], 0, s[34:35]
	global_load_dwordx4 v[96:99], v[44:45], off
	global_load_dwordx4 v[100:103], v[44:45], off offset:1024
	global_load_dwordx4 v[104:107], v[44:45], off offset:2048
	global_load_dwordx4 v[108:111], v[44:45], off offset:3072
	s_waitcnt vmcnt(12)
	v_pk_add_f32 v[26:27], v[26:27], v[48:49]
	v_pk_add_f32 v[28:29], v[28:29], v[50:51]
	v_pk_add_f32 v[22:23], v[22:23], v[52:53]
	v_pk_add_f32 v[24:25], v[24:25], v[54:55]
	v_pk_add_f32 v[18:19], v[18:19], v[56:57]
	v_pk_add_f32 v[20:21], v[20:21], v[58:59]
	v_pk_add_f32 v[30:31], v[30:31], v[60:61]
	v_pk_add_f32 v[32:33], v[32:33], v[62:63]
	s_waitcnt vmcnt(8)
	v_pk_add_f32 v[26:27], v[26:27], v[64:65]
	v_pk_add_f32 v[28:29], v[28:29], v[66:67]
	v_pk_add_f32 v[22:23], v[22:23], v[68:69]
	v_pk_add_f32 v[24:25], v[24:25], v[70:71]
	v_pk_add_f32 v[18:19], v[18:19], v[72:73]
	v_pk_add_f32 v[20:21], v[20:21], v[74:75]
	v_pk_add_f32 v[30:31], v[30:31], v[76:77]
	v_pk_add_f32 v[32:33], v[32:33], v[78:79]
	s_waitcnt vmcnt(4)
	v_pk_add_f32 v[26:27], v[26:27], v[80:81]
	v_pk_add_f32 v[28:29], v[28:29], v[82:83]
	v_pk_add_f32 v[22:23], v[22:23], v[84:85]
	v_pk_add_f32 v[24:25], v[24:25], v[86:87]
	v_pk_add_f32 v[18:19], v[18:19], v[88:89]
	v_pk_add_f32 v[20:21], v[20:21], v[90:91]
	v_pk_add_f32 v[30:31], v[30:31], v[92:93]
	v_pk_add_f32 v[32:33], v[32:33], v[94:95]
	s_waitcnt vmcnt(0)
	v_pk_add_f32 v[26:27], v[26:27], v[96:97]
	v_pk_add_f32 v[28:29], v[28:29], v[98:99]
	v_pk_add_f32 v[22:23], v[22:23], v[100:101]
	v_pk_add_f32 v[24:25], v[24:25], v[102:103]
	v_pk_add_f32 v[18:19], v[18:19], v[104:105]
	v_pk_add_f32 v[20:21], v[20:21], v[106:107]
	v_pk_add_f32 v[30:31], v[30:31], v[108:109]
	v_pk_add_f32 v[32:33], v[32:33], v[110:111]
	global_store_dwordx4 v[40:41], v[26:29], off
	global_store_dwordx4 v[40:41], v[22:25], off offset:1024
	global_store_dwordx4 v[40:41], v[18:21], off offset:2048
	global_store_dwordx4 v[40:41], v[30:33], off offset:3072
	s_branch .LBB0_20

; __device__ __forceinline__ void norm_phase(const float* hl, const float* hc, const float* __restrict__ g, const float* __restrict__ modl, int sh_chunk, bf16_t* XN, int gw, int NGW, int lane, int nrows, const float* part, int npieces) {
;     ...
;         const float* xr = row < MLAT ? hl + (size_t)row * D : hc + (size_t)(row - MLAT) * D;
;         const int mi = row < MLAT ? (row >> 13) : 4;
;         const float* shift = modl + mi * 9216 + sh_chunk * 1024; const float* scale = shift + 1024;
;         f32x4 v[4]; float s = 0.f;
; #pragma unroll
;         for (int j = 0; j < 4; ++j) v[j] = *(const f32x4*)(xr + 4 * lane + 256 * j);
;         if (row >= MLAT && npieces > 0) {
;             for (int p = 0; p < npieces; ++p) { const float* pr = part + ((size_t)p * 1024 + (row - MLAT)) * D + 4 * lane;
; #pragma unroll
;                 for (int j = 0; j < 4; ++j) v[j] = v[j] + *(const f32x4*)(pr + 256 * j); }
; #pragma unroll
;             for (int j = 0; j < 4; ++j) *(f32x4*)(const_cast<float*>(xr) + 4 * lane + 256 * j) = v[j];
;         }
.LBB0_32:
	s_add_i32 s16, s2, 0xffff8000
	s_ashr_i32 s3, s2, 31
	s_cmp_lt_i32 s2, 0x8000
	s_cselect_b64 s[20:21], -1, 0
	s_and_b64 vcc, s[20:21], exec
	s_cselect_b32 s21, s3, 0
	s_cselect_b32 s20, s2, s16
	s_cselect_b32 s15, s9, s37
	s_cselect_b32 s26, s8, s36
	s_lshl_b64 s[20:21], s[20:21], 12
	s_add_u32 s20, s26, s20
	s_addc_u32 s21, s15, s21
	v_lshl_add_u64 v[40:41], v[34:35], 2, s[20:21]
	global_load_dwordx4 v[26:29], v[40:41], off
	global_load_dwordx4 v[22:25], v[40:41], off offset:1024
	global_load_dwordx4 v[18:21], v[40:41], off offset:2048
	global_load_dwordx4 v[30:33], v[40:41], off offset:3072
	s_cbranch_vccnz .LBB0_31
	s_lshl_b64 s[20:21], s[16:17], 12
	v_lshl_add_u64 v[42:43], v[36:37], 0, s[20:21]
	s_mov_b32 s21, 0
	global_load_dwordx4 v[48:51], v[42:43], off
	global_load_dwordx4 v[52:55], v[42:43], off offset:1024
	global_load_dwordx4 v[56:59], v[42:43], off offset:2048
	global_load_dwordx4 v[60:63], v[42:43], off offset:3072
	s_mov_b32 s20, 0x400000
	v_lshl_add_u64 v[44:45], v[42:43], 0, s[20:21]
	global_load_dwordx4 v[64:67], v[44:45], off
	global_load_dwordx4 v[68:71], v[44:45], off offset:1024
	global_load_dwordx4 v[72:75], v[44:45], off offset:2048
	global_load_dwordx4 v[76:79], v[44:45], off offset:3072
	s_mov_b32 s20, 0x800000
	v_lshl_add_u64 v[46:47], v[42:43], 0, s[20:21]
	global_load_dwordx4 v[80:83], v[46:47], off
	global_load_dwordx4 v[84:87], v[46:47], off offset:1024
	global_load_dwordx4 v[88:91], v[46:47], off offset:2048
	global_load_dwordx4 v[92:95], v[46:47], off offset:3072
	s_mov_b32 s20, 0xc00000
	v_lshl_add_u64 v[44:45], v[42:43], 0, s[20:21]
	global_load_dwordx4 v[96:99], v[44:45], off
	global_load_dwordx4 v[100:103], v[44:45], off offset:1024
	global_load_dwordx4 v[104:107], v[44:45], off offset:2048
	global_load_dwordx4 v[108:111], v[44:45], off offset:3072
	s_mov_b32 s20, 0x1000000
	v_lshl_add_u64 v[46:47], v[42:43], 0, s[20:21]
	global_load_dwordx4 v[112:115], v[46:47], off
	global_load_dwordx4 v[116:119], v[46:47], off offset:1024
	global_load_dwordx4 v[120:123], v[46:47], off offset:2048
	global_load_dwordx4 v[124:127], v[46:47], off offset:3072
	s_mov_b32 s20, 0x1400000
	v_lshl_add_u64 v[44:45], v[42:43], 0, s[20:21]
	global_load_dwordx4 v[128:131], v[44:45], off
	global_load_dwordx4 v[132:135], v[44:45], off offset:1024
	global_load_dwordx4 v[136:139], v[44:45], off offset:2048
	global_load_dwordx4 v[140:143], v[44:45], off offset:3072
	s_mov_b32 s20, 0x1800000
	v_lshl_add_u64 v[46:47], v[42:43], 0, s[20:21]
	global_load_dwordx4 v[144:147], v[46:47], off
	global_load_dwordx4 v[148:151], v[46:47], off offset:1024
	global_load_dwordx4 v[152:155], v[46:47], off offset:2048
	global_load_dwordx4 v[156:159], v[46:47], off offset:3072
	s_mov_b32 s20, 0x1c00000
	v_lshl_add_u64 v[44:45], v[42:43], 0, s[20:21]
	global_load_dwordx4 v[160:163], v[44:45], off
	global_load_dwordx4 v[164:167], v[44:45], off offset:1024
	global_load_dwordx4 v[168:171], v[44:45], off offset:2048
	global_load_dwordx4 v[172:175], v[44:45], off offset:3072
	s_mov_b32 s20, 0x2000000
	v_lshl_add_u64 v[46:47], v[42:43], 0, s[20:21]
	global_load_dwordx4 v[176:179], v[46:47], off
	global_load_dwordx4 v[180:183], v[46:47], off offset:1024
	global_load_dwordx4 v[184:187], v[46:47], off offset:2048
	global_load_dwordx4 v[192:195], v[46:47], off offset:3072
	s_mov_b32 s20, 0x2400000
	v_lshl_add_u64 v[44:45], v[42:43], 0, s[20:21]
	global_load_dwordx4 v[196:199], v[44:45], off
	global_load_dwordx4 v[200:203], v[44:45], off offset:1024
	global_load_dwordx4 v[218:221], v[44:45], off offset:2048
	global_load_dwordx4 v[222:225], v[44:45], off offset:3072
	s_mov_b32 s20, 0x2800000
	v_lshl_add_u64 v[46:47], v[42:43], 0, s[20:21]
	global_load_dwordx4 v[230:233], v[46:47], off
	global_load_dwordx4 v[234:237], v[46:47], off offset:1024
	global_load_dwordx4 v[238:241], v[46:47], off offset:2048
	global_load_dwordx4 v[242:245], v[46:47], off offset:3072
	s_waitcnt vmcnt(40)
	v_pk_add_f32 v[26:27], v[26:27], v[48:49]
	v_pk_add_f32 v[28:29], v[28:29], v[50:51]
	v_pk_add_f32 v[22:23], v[22:23], v[52:53]
	v_pk_add_f32 v[24:25], v[24:25], v[54:55]
	v_pk_add_f32 v[18:19], v[18:19], v[56:57]
	v_pk_add_f32 v[20:21], v[20:21], v[58:59]
	v_pk_add_f32 v[30:31], v[30:31], v[60:61]
	v_pk_add_f32 v[32:33], v[32:33], v[62:63]
	s_waitcnt vmcnt(36)
; __device__ __forceinline__ void norm_phase(const float* hl, const float* hc, const float* __restrict__ g, const float* __restrict__ modl, int sh_chunk, bf16_t* XN, int gw, int NGW, int lane, int nrows, const float* part, int npieces) {
;     ...
;         if (row >= MLAT && npieces > 0) {
;             for (int p = 0; p < npieces; ++p) { const float* pr = part + ((size_t)p * 1024 + (row - MLAT)) * D + 4 * lane;
; #pragma unroll
;                 for (int j = 0; j < 4; ++j) v[j] = v[j] + *(const f32x4*)(pr + 256 * j); }
; #pragma unroll
;             for (int j = 0; j < 4; ++j) *(f32x4*)(const_cast<float*>(xr) + 4 * lane + 256 * j) = v[j];
;         }
	v_pk_add_f32 v[26:27], v[26:27], v[64:65]
	v_pk_add_f32 v[28:29], v[28:29], v[66:67]
	v_pk_add_f32 v[22:23], v[22:23], v[68:69]
	v_pk_add_f32 v[24:25], v[24:25], v[70:71]
	v_pk_add_f32 v[18:19], v[18:19], v[72:73]
	v_pk_add_f32 v[20:21], v[20:21], v[74:75]
	v_pk_add_f32 v[30:31], v[30:31], v[76:77]
	v_pk_add_f32 v[32:33], v[32:33], v[78:79]
	s_waitcnt vmcnt(32)
	v_pk_add_f32 v[26:27], v[26:27], v[80:81]
	v_pk_add_f32 v[28:29], v[28:29], v[82:83]
	v_pk_add_f32 v[22:23], v[22:23], v[84:85]
	v_pk_add_f32 v[24:25], v[24:25], v[86:87]
	v_pk_add_f32 v[18:19], v[18:19], v[88:89]
	v_pk_add_f32 v[20:21], v[20:21], v[90:91]
	v_pk_add_f32 v[30:31], v[30:31], v[92:93]
	v_pk_add_f32 v[32:33], v[32:33], v[94:95]
	s_waitcnt vmcnt(28)
	v_pk_add_f32 v[26:27], v[26:27], v[96:97]
	v_pk_add_f32 v[28:29], v[28:29], v[98:99]
	v_pk_add_f32 v[22:23], v[22:23], v[100:101]
	v_pk_add_f32 v[24:25], v[24:25], v[102:103]
	v_pk_add_f32 v[18:19], v[18:19], v[104:105]
	v_pk_add_f32 v[20:21], v[20:21], v[106:107]
	v_pk_add_f32 v[30:31], v[30:31], v[108:109]
	v_pk_add_f32 v[32:33], v[32:33], v[110:111]
	s_waitcnt vmcnt(24)
	v_pk_add_f32 v[26:27], v[26:27], v[112:113]
	v_pk_add_f32 v[28:29], v[28:29], v[114:115]
	v_pk_add_f32 v[22:23], v[22:23], v[116:117]
	v_pk_add_f32 v[24:25], v[24:25], v[118:119]
	v_pk_add_f32 v[18:19], v[18:19], v[120:121]
	v_pk_add_f32 v[20:21], v[20:21], v[122:123]
	v_pk_add_f32 v[30:31], v[30:31], v[124:125]
	v_pk_add_f32 v[32:33], v[32:33], v[126:127]
	s_waitcnt vmcnt(20)
	v_pk_add_f32 v[26:27], v[26:27], v[128:129]
	v_pk_add_f32 v[28:29], v[28:29], v[130:131]
	v_pk_add_f32 v[22:23], v[22:23], v[132:133]
	v_pk_add_f32 v[24:25], v[24:25], v[134:135]
	v_pk_add_f32 v[18:19], v[18:19], v[136:137]
	v_pk_add_f32 v[20:21], v[20:21], v[138:139]
	v_pk_add_f32 v[30:31], v[30:31], v[140:141]
	v_pk_add_f32 v[32:33], v[32:33], v[142:143]
	s_waitcnt vmcnt(16)
	v_pk_add_f32 v[26:27], v[26:27], v[144:145]
	v_pk_add_f32 v[28:29], v[28:29], v[146:147]
	v_pk_add_f32 v[22:23], v[22:23], v[148:149]
	v_pk_add_f32 v[24:25], v[24:25], v[150:151]
	v_pk_add_f32 v[18:19], v[18:19], v[152:153]
	v_pk_add_f32 v[20:21], v[20:21], v[154:155]
	v_pk_add_f32 v[30:31], v[30:31], v[156:157]
	v_pk_add_f32 v[32:33], v[32:33], v[158:159]
	s_waitcnt vmcnt(12)
	v_pk_add_f32 v[26:27], v[26:27], v[160:161]
	v_pk_add_f32 v[28:29], v[28:29], v[162:163]
	v_pk_add_f32 v[22:23], v[22:23], v[164:165]
	v_pk_add_f32 v[24:25], v[24:25], v[166:167]
	v_pk_add_f32 v[18:19], v[18:19], v[168:169]
	v_pk_add_f32 v[20:21], v[20:21], v[170:171]
	v_pk_add_f32 v[30:31], v[30:31], v[172:173]
	v_pk_add_f32 v[32:33], v[32:33], v[174:175]
	s_waitcnt vmcnt(8)
	v_pk_add_f32 v[26:27], v[26:27], v[176:177]
	v_pk_add_f32 v[28:29], v[28:29], v[178:179]
	v_pk_add_f32 v[22:23], v[22:23], v[180:181]
	v_pk_add_f32 v[24:25], v[24:25], v[182:183]
	v_pk_add_f32 v[18:19], v[18:19], v[184:185]
	v_pk_add_f32 v[20:21], v[20:21], v[186:187]
	v_pk_add_f32 v[30:31], v[30:31], v[192:193]
	v_pk_add_f32 v[32:33], v[32:33], v[194:195]
	s_waitcnt vmcnt(4)
	v_pk_add_f32 v[26:27], v[26:27], v[196:197]
	v_pk_add_f32 v[28:29], v[28:29], v[198:199]
	v_pk_add_f32 v[22:23], v[22:23], v[200:201]
	v_pk_add_f32 v[24:25], v[24:25], v[202:203]
	v_pk_add_f32 v[18:19], v[18:19], v[218:219]
	v_pk_add_f32 v[20:21], v[20:21], v[220:221]
	v_pk_add_f32 v[30:31], v[30:31], v[222:223]
	v_pk_add_f32 v[32:33], v[32:33], v[224:225]
	s_waitcnt vmcnt(0)
	v_pk_add_f32 v[26:27], v[26:27], v[230:231]
	v_pk_add_f32 v[28:29], v[28:29], v[232:233]
	v_pk_add_f32 v[22:23], v[22:23], v[234:235]
	v_pk_add_f32 v[24:25], v[24:25], v[236:237]
	v_pk_add_f32 v[18:19], v[18:19], v[238:239]
	v_pk_add_f32 v[20:21], v[20:21], v[240:241]
	v_pk_add_f32 v[30:31], v[30:31], v[242:243]
	v_pk_add_f32 v[32:33], v[32:33], v[244:245]
	global_store_dwordx4 v[40:41], v[26:29], off
	global_store_dwordx4 v[40:41], v[22:25], off offset:1024
	global_store_dwordx4 v[40:41], v[18:21], off offset:2048
	global_store_dwordx4 v[40:41], v[30:33], off offset:3072
	s_branch .LBB0_31

; __device__ __forceinline__ void norm_phase(const float* hl, const float* hc, const float* __restrict__ g, const float* __restrict__ modl, int sh_chunk, bf16_t* XN, int gw, int NGW, int lane, int nrows, const float* part, int npieces) {
;     ...
;         const float* xr = row < MLAT ? hl + (size_t)row * D : hc + (size_t)(row - MLAT) * D;
;         const int mi = row < MLAT ? (row >> 13) : 4;
;         const float* shift = modl + mi * 9216 + sh_chunk * 1024; const float* scale = shift + 1024;
;         f32x4 v[4]; float s = 0.f;
; #pragma unroll
;         for (int j = 0; j < 4; ++j) v[j] = *(const f32x4*)(xr + 4 * lane + 256 * j);
;         if (row >= MLAT && npieces > 0) {
;             for (int p = 0; p < npieces; ++p) { const float* pr = part + ((size_t)p * 1024 + (row - MLAT)) * D + 4 * lane;
; #pragma unroll
;                 for (int j = 0; j < 4; ++j) v[j] = v[j] + *(const f32x4*)(pr + 256 * j); }
; #pragma unroll
;             for (int j = 0; j < 4; ++j) *(f32x4*)(const_cast<float*>(xr) + 4 * lane + 256 * j) = v[j];
;         }
.LBB0_1088:
	s_add_i32 s16, s0, 0xffff8000
	s_ashr_i32 s1, s0, 31
	s_cmp_lt_i32 s0, 0x8000
	s_cselect_b64 s[12:13], -1, 0
	s_and_b64 s[14:15], s[12:13], exec
	s_cselect_b32 s15, s1, 0
	s_cselect_b32 s14, s0, s16
	s_cselect_b32 s20, s9, s37
	s_cselect_b32 s21, s8, s36
	s_lshl_b64 s[14:15], s[14:15], 12
	s_add_u32 s14, s21, s14
	s_addc_u32 s15, s20, s15
	v_lshl_add_u64 v[40:41], v[34:35], 2, s[14:15]
	global_load_dwordx4 v[26:29], v[40:41], off
	global_load_dwordx4 v[22:25], v[40:41], off offset:1024
	global_load_dwordx4 v[18:21], v[40:41], off offset:2048
	global_load_dwordx4 v[30:33], v[40:41], off offset:3072
	s_or_b64 s[12:13], s[2:3], s[12:13]
	s_and_b64 vcc, exec, s[12:13]
	s_cbranch_vccnz .LBB0_1087
	s_lshl_b64 s[12:13], s[16:17], 12
	v_lshl_add_u64 v[42:43], v[36:37], 0, s[12:13]
	s_mov_b32 s13, 0
	global_load_dwordx4 v[48:51], v[42:43], off
	global_load_dwordx4 v[52:55], v[42:43], off offset:1024
	global_load_dwordx4 v[56:59], v[42:43], off offset:2048
	global_load_dwordx4 v[60:63], v[42:43], off offset:3072
	s_mov_b32 s12, 0x400000
	v_lshl_add_u64 v[44:45], v[42:43], 0, s[12:13]
	global_load_dwordx4 v[64:67], v[44:45], off
	global_load_dwordx4 v[68:71], v[44:45], off offset:1024
	global_load_dwordx4 v[72:75], v[44:45], off offset:2048
	global_load_dwordx4 v[76:79], v[44:45], off offset:3072
	s_mov_b32 s12, 0x800000
	v_lshl_add_u64 v[46:47], v[42:43], 0, s[12:13]
	global_load_dwordx4 v[80:83], v[46:47], off
	global_load_dwordx4 v[84:87], v[46:47], off offset:1024
	global_load_dwordx4 v[88:91], v[46:47], off offset:2048
	global_load_dwordx4 v[92:95], v[46:47], off offset:3072
	s_mov_b32 s12, 0xc00000
	v_lshl_add_u64 v[44:45], v[42:43], 0, s[12:13]
	global_load_dwordx4 v[96:99], v[44:45], off
	global_load_dwordx4 v[100:103], v[44:45], off offset:1024
	global_load_dwordx4 v[104:107], v[44:45], off offset:2048
	global_load_dwordx4 v[108:111], v[44:45], off offset:3072
	s_mov_b32 s12, 0x1000000
	v_lshl_add_u64 v[46:47], v[42:43], 0, s[12:13]
	global_load_dwordx4 v[112:115], v[46:47], off
	global_load_dwordx4 v[116:119], v[46:47], off offset:1024
	global_load_dwordx4 v[120:123], v[46:47], off offset:2048
	global_load_dwordx4 v[124:127], v[46:47], off offset:3072
	s_mov_b32 s12, 0x1400000
	v_lshl_add_u64 v[44:45], v[42:43], 0, s[12:13]
	global_load_dwordx4 v[128:131], v[44:45], off
	global_load_dwordx4 v[132:135], v[44:45], off offset:1024
	global_load_dwordx4 v[136:139], v[44:45], off offset:2048
	global_load_dwordx4 v[140:143], v[44:45], off offset:3072
	s_mov_b32 s12, 0x1800000
	v_lshl_add_u64 v[46:47], v[42:43], 0, s[12:13]
	global_load_dwordx4 v[144:147], v[46:47], off
	global_load_dwordx4 v[148:151], v[46:47], off offset:1024
	global_load_dwordx4 v[152:155], v[46:47], off offset:2048
	global_load_dwordx4 v[156:159], v[46:47], off offset:3072
	s_mov_b32 s12, 0x1c00000
	v_lshl_add_u64 v[44:45], v[42:43], 0, s[12:13]
	global_load_dwordx4 v[160:163], v[44:45], off
	global_load_dwordx4 v[164:167], v[44:45], off offset:1024
	global_load_dwordx4 v[168:171], v[44:45], off offset:2048
	global_load_dwordx4 v[172:175], v[44:45], off offset:3072
	s_mov_b32 s12, 0x2000000
	v_lshl_add_u64 v[46:47], v[42:43], 0, s[12:13]
	global_load_dwordx4 v[176:179], v[46:47], off
	global_load_dwordx4 v[180:183], v[46:47], off offset:1024
	global_load_dwordx4 v[184:187], v[46:47], off offset:2048
	global_load_dwordx4 v[192:195], v[46:47], off offset:3072
	s_mov_b32 s12, 0x2400000
	v_lshl_add_u64 v[44:45], v[42:43], 0, s[12:13]
	global_load_dwordx4 v[196:199], v[44:45], off
	global_load_dwordx4 v[200:203], v[44:45], off offset:1024
	global_load_dwordx4 v[218:221], v[44:45], off offset:2048
	global_load_dwordx4 v[222:225], v[44:45], off offset:3072
	s_mov_b32 s12, 0x2800000
	v_lshl_add_u64 v[46:47], v[42:43], 0, s[12:13]
	global_load_dwordx4 v[230:233], v[46:47], off
	global_load_dwordx4 v[234:237], v[46:47], off offset:1024
	global_load_dwordx4 v[238:241], v[46:47], off offset:2048
	global_load_dwordx4 v[242:245], v[46:47], off offset:3072
	s_waitcnt vmcnt(40)
; __device__ __forceinline__ void norm_phase(const float* hl, const float* hc, const float* __restrict__ g, const float* __restrict__ modl, int sh_chunk, bf16_t* XN, int gw, int NGW, int lane, int nrows, const float* part, int npieces) {
;     ...
;         if (row >= MLAT && npieces > 0) {
;             for (int p = 0; p < npieces; ++p) { const float* pr = part + ((size_t)p * 1024 + (row - MLAT)) * D + 4 * lane;
; #pragma unroll
;                 for (int j = 0; j < 4; ++j) v[j] = v[j] + *(const f32x4*)(pr + 256 * j); }
; #pragma unroll
;             for (int j = 0; j < 4; ++j) *(f32x4*)(const_cast<float*>(xr) + 4 * lane + 256 * j) = v[j];
;         }
	v_pk_add_f32 v[26:27], v[26:27], v[48:49]
	v_pk_add_f32 v[28:29], v[28:29], v[50:51]
	v_pk_add_f32 v[22:23], v[22:23], v[52:53]
	v_pk_add_f32 v[24:25], v[24:25], v[54:55]
	v_pk_add_f32 v[18:19], v[18:19], v[56:57]
	v_pk_add_f32 v[20:21], v[20:21], v[58:59]
	v_pk_add_f32 v[30:31], v[30:31], v[60:61]
	v_pk_add_f32 v[32:33], v[32:33], v[62:63]
	s_waitcnt vmcnt(36)
	v_pk_add_f32 v[26:27], v[26:27], v[64:65]
	v_pk_add_f32 v[28:29], v[28:29], v[66:67]
	v_pk_add_f32 v[22:23], v[22:23], v[68:69]
	v_pk_add_f32 v[24:25], v[24:25], v[70:71]
	v_pk_add_f32 v[18:19], v[18:19], v[72:73]
	v_pk_add_f32 v[20:21], v[20:21], v[74:75]
	v_pk_add_f32 v[30:31], v[30:31], v[76:77]
	v_pk_add_f32 v[32:33], v[32:33], v[78:79]
	s_waitcnt vmcnt(32)
	v_pk_add_f32 v[26:27], v[26:27], v[80:81]
	v_pk_add_f32 v[28:29], v[28:29], v[82:83]
	v_pk_add_f32 v[22:23], v[22:23], v[84:85]
	v_pk_add_f32 v[24:25], v[24:25], v[86:87]
	v_pk_add_f32 v[18:19], v[18:19], v[88:89]
	v_pk_add_f32 v[20:21], v[20:21], v[90:91]
	v_pk_add_f32 v[30:31], v[30:31], v[92:93]
	v_pk_add_f32 v[32:33], v[32:33], v[94:95]
	s_waitcnt vmcnt(28)
	v_pk_add_f32 v[26:27], v[26:27], v[96:97]
	v_pk_add_f32 v[28:29], v[28:29], v[98:99]
	v_pk_add_f32 v[22:23], v[22:23], v[100:101]
	v_pk_add_f32 v[24:25], v[24:25], v[102:103]
	v_pk_add_f32 v[18:19], v[18:19], v[104:105]
	v_pk_add_f32 v[20:21], v[20:21], v[106:107]
	v_pk_add_f32 v[30:31], v[30:31], v[108:109]
	v_pk_add_f32 v[32:33], v[32:33], v[110:111]
	s_waitcnt vmcnt(24)
	v_pk_add_f32 v[26:27], v[26:27], v[112:113]
	v_pk_add_f32 v[28:29], v[28:29], v[114:115]
	v_pk_add_f32 v[22:23], v[22:23], v[116:117]
	v_pk_add_f32 v[24:25], v[24:25], v[118:119]
	v_pk_add_f32 v[18:19], v[18:19], v[120:121]
	v_pk_add_f32 v[20:21], v[20:21], v[122:123]
	v_pk_add_f32 v[30:31], v[30:31], v[124:125]
	v_pk_add_f32 v[32:33], v[32:33], v[126:127]
	s_waitcnt vmcnt(20)
	v_pk_add_f32 v[26:27], v[26:27], v[128:129]
	v_pk_add_f32 v[28:29], v[28:29], v[130:131]
	v_pk_add_f32 v[22:23], v[22:23], v[132:133]
	v_pk_add_f32 v[24:25], v[24:25], v[134:135]
	v_pk_add_f32 v[18:19], v[18:19], v[136:137]
	v_pk_add_f32 v[20:21], v[20:21], v[138:139]
	v_pk_add_f32 v[30:31], v[30:31], v[140:141]
	v_pk_add_f32 v[32:33], v[32:33], v[142:143]
	s_waitcnt vmcnt(16)
	v_pk_add_f32 v[26:27], v[26:27], v[144:145]
	v_pk_add_f32 v[28:29], v[28:29], v[146:147]
	v_pk_add_f32 v[22:23], v[22:23], v[148:149]
	v_pk_add_f32 v[24:25], v[24:25], v[150:151]
	v_pk_add_f32 v[18:19], v[18:19], v[152:153]
	v_pk_add_f32 v[20:21], v[20:21], v[154:155]
	v_pk_add_f32 v[30:31], v[30:31], v[156:157]
	v_pk_add_f32 v[32:33], v[32:33], v[158:159]
	s_waitcnt vmcnt(12)
	v_pk_add_f32 v[26:27], v[26:27], v[160:161]
	v_pk_add_f32 v[28:29], v[28:29], v[162:163]
	v_pk_add_f32 v[22:23], v[22:23], v[164:165]
	v_pk_add_f32 v[24:25], v[24:25], v[166:167]
	v_pk_add_f32 v[18:19], v[18:19], v[168:169]
	v_pk_add_f32 v[20:21], v[20:21], v[170:171]
	v_pk_add_f32 v[30:31], v[30:31], v[172:173]
	v_pk_add_f32 v[32:33], v[32:33], v[174:175]
	s_waitcnt vmcnt(8)
	v_pk_add_f32 v[26:27], v[26:27], v[176:177]
	v_pk_add_f32 v[28:29], v[28:29], v[178:179]
	v_pk_add_f32 v[22:23], v[22:23], v[180:181]
	v_pk_add_f32 v[24:25], v[24:25], v[182:183]
	v_pk_add_f32 v[18:19], v[18:19], v[184:185]
	v_pk_add_f32 v[20:21], v[20:21], v[186:187]
	v_pk_add_f32 v[30:31], v[30:31], v[192:193]
	v_pk_add_f32 v[32:33], v[32:33], v[194:195]
	s_waitcnt vmcnt(4)
	v_pk_add_f32 v[26:27], v[26:27], v[196:197]
	v_pk_add_f32 v[28:29], v[28:29], v[198:199]
	v_pk_add_f32 v[22:23], v[22:23], v[200:201]
	v_pk_add_f32 v[24:25], v[24:25], v[202:203]
	v_pk_add_f32 v[18:19], v[18:19], v[218:219]
	v_pk_add_f32 v[20:21], v[20:21], v[220:221]
	v_pk_add_f32 v[30:31], v[30:31], v[222:223]
	v_pk_add_f32 v[32:33], v[32:33], v[224:225]
	s_waitcnt vmcnt(0)
	v_pk_add_f32 v[26:27], v[26:27], v[230:231]
	v_pk_add_f32 v[28:29], v[28:29], v[232:233]
	v_pk_add_f32 v[22:23], v[22:23], v[234:235]
	v_pk_add_f32 v[24:25], v[24:25], v[236:237]
	v_pk_add_f32 v[18:19], v[18:19], v[238:239]
	v_pk_add_f32 v[20:21], v[20:21], v[240:241]
	v_pk_add_f32 v[30:31], v[30:31], v[242:243]
	v_pk_add_f32 v[32:33], v[32:33], v[244:245]
	global_store_dwordx4 v[40:41], v[26:29], off
	global_store_dwordx4 v[40:41], v[22:25], off offset:1024
	global_store_dwordx4 v[40:41], v[18:21], off offset:2048
	global_store_dwordx4 v[40:41], v[30:33], off offset:3072
	s_branch .LBB0_1087
